# diff-attention S loop: back edge rotated in front of the loop barrier, max-tree canonicalising self-max ops removed, on top of K-fragment address trim
# speedup vs baseline: 1.0006x; 1.0006x over previous
.LBB0_1359:
	s_addk_i32 s18, 0x80
	s_add_i32 s72, s72, 0x8000
	s_add_i32 s70, s70, 2
	s_add_i32 s69, s69, 2
	s_add_i32 s68, s68, 2
	s_add_i32 s71, s71, 2
	s_cmp_ge_u32 s20, s36
	s_cbranch_scc1 .Lrot_exit_0
	s_waitcnt lgkmcnt(0)
	s_barrier
.LBB0_1360:
	v_max_f32_e32 v101, v4, v5
	v_max3_f32 v101, v101, v6, v7
	v_max3_f32 v101, v101, v8, v9
	v_max3_f32 v101, v101, v10, v11
	v_max3_f32 v101, v101, v12, v13
	v_max3_f32 v101, v101, v14, v15
	v_max3_f32 v101, v101, v16, v17
	v_max3_f32 v101, v101, v18, v19
	v_max3_f32 v101, v101, v20, v21
	v_max3_f32 v101, v101, v22, v23
	v_max3_f32 v101, v101, v24, v25
	v_max3_f32 v101, v101, v26, v27
	v_max3_f32 v101, v101, v28, v29
	v_max3_f32 v101, v101, v30, v31
	v_max3_f32 v101, v101, v32, v33
	v_max3_f32 v101, v101, v34, v35
	v_mov_b32_e32 v103, v101
	s_nop 1
	v_permlane32_swap_b32_e32 v101, v103
	v_max_f32_e32 v101, v101, v103
	v_sub_f32_e32 v103, v101, v102
	v_cmp_ge_f32_e32 vcc, s34, v103
	v_max_f32_e32 v103, v102, v101
	v_sub_f32_e32 v101, v102, v103
	v_mul_f32_e32 v101, 0x3fb8aa3b, v101
	v_exp_f32_e32 v101, v101
	s_cmp_eq_u64 vcc, exec
	s_cselect_b64 vcc, -1, 0
	v_cndmask_b32_e64 v101, v101, 1.0, vcc
	v_cmp_gt_f32_e64 s[0:1], 1.0, v101
	s_cmp_lg_u64 s[0:1], 0
	s_cselect_b64 s[0:1], -1, 0
	s_and_b64 s[78:79], s[0:1], s[2:3]
	s_and_saveexec_b64 s[20:21], s[78:79]
	ds_write_b32 v2, v101
	s_or_b64 exec, exec, s[20:21]
	s_and_saveexec_b64 s[20:21], s[4:5]
	v_cndmask_b32_e64 v104, 0, 1, s[0:1]
	s_add_i32 s0, s59, 0
	s_add_i32 s0, s0, 0x20000
	v_mov_b32_e32 v105, s0
	ds_write_b32 v105, v104
	s_or_b64 exec, exec, s[20:21]
	s_add_i32 s0, s70, -3
	s_cmp_ge_u32 s0, s36
	v_add_u32_e32 v104, s72, v184
	s_cbranch_scc1 .LBB0_1366
	s_mul_hi_u32 s0, s68, 0xaaaaaaab
	s_lshr_b32 s0, s0, 1
	s_mul_i32 s0, s0, 0xc000
	s_sub_i32 s98, s72, s0
	v_add_u32_e32 v251, s98, v184
	v_add_u32_e32 v47, v251, v190
	v_add_u32_e32 v40, v251, v192
	v_add_u32_e32 v41, v251, v194
	v_add_u32_e32 v42, v251, v196
	v_add_u32_e32 v43, v251, v198
	v_add_u32_e32 v44, v251, v200
	v_add_u32_e32 v45, v251, v202
	v_add_u32_e32 v46, v251, v203
	ds_read_b128 v[36:39], v47
	ds_read_b128 v[106:109], v40
	ds_read_b128 v[114:117], v41
	ds_read_b128 v[122:125], v42
	ds_read_b128 v[130:133], v43
	ds_read_b128 v[138:141], v44
	ds_read_b128 v[146:149], v45
	ds_read_b128 v[214:217], v46
	ds_read_b128 v[52:55], v47 offset:8192
	ds_read_b128 v[110:113], v40 offset:8192
	ds_read_b128 v[118:121], v41 offset:8192
	ds_read_b128 v[126:129], v42 offset:8192
	ds_read_b128 v[134:137], v43 offset:8192
	ds_read_b128 v[142:145], v44 offset:8192
	ds_read_b128 v[150:153], v45 offset:8192
	ds_read_b128 v[218:221], v46 offset:8192
	s_waitcnt lgkmcnt(14)
	v_mfma_f32_32x32x16_bf16 v[36:51], v[36:39], v[68:71], 0
	v_cndmask_b32_e32 v102, v103, v102, vcc
	v_mul_f32_e32 v103, 0xbfb8aa3b, v102
	v_fmamk_f32 v4, v4, 0x3fb8aa3b, v103
	v_fmamk_f32 v5, v5, 0x3fb8aa3b, v103
	v_exp_f32_e32 v4, v4
	v_fmamk_f32 v6, v6, 0x3fb8aa3b, v103
	v_exp_f32_e32 v5, v5
	v_mfma_f32_32x32x16_bf16 v[36:51], v[106:109], v[72:75], v[36:51]
	v_fmamk_f32 v7, v7, 0x3fb8aa3b, v103
	v_exp_f32_e32 v6, v6
	v_fmamk_f32 v8, v8, 0x3fb8aa3b, v103
	v_fmamk_f32 v9, v9, 0x3fb8aa3b, v103
	v_fmamk_f32 v10, v10, 0x3fb8aa3b, v103
	v_fmamk_f32 v11, v11, 0x3fb8aa3b, v103
	v_fmamk_f32 v12, v12, 0x3fb8aa3b, v103
	s_waitcnt lgkmcnt(13)
	v_mfma_f32_32x32x16_bf16 v[36:51], v[114:117], v[76:79], v[36:51]
	v_fmamk_f32 v13, v13, 0x3fb8aa3b, v103
	v_fmamk_f32 v14, v14, 0x3fb8aa3b, v103
	v_fmamk_f32 v15, v15, 0x3fb8aa3b, v103
	v_fmamk_f32 v16, v16, 0x3fb8aa3b, v103
	v_fmamk_f32 v17, v17, 0x3fb8aa3b, v103
	v_fmamk_f32 v18, v18, 0x3fb8aa3b, v103
	v_fmamk_f32 v19, v19, 0x3fb8aa3b, v103
	v_fmamk_f32 v20, v20, 0x3fb8aa3b, v103
	s_waitcnt lgkmcnt(12)
	v_mfma_f32_32x32x16_bf16 v[36:51], v[122:125], v[80:83], v[36:51]
	v_fmamk_f32 v21, v21, 0x3fb8aa3b, v103
	v_fmamk_f32 v22, v22, 0x3fb8aa3b, v103
	v_fmamk_f32 v23, v23, 0x3fb8aa3b, v103
	v_fmamk_f32 v24, v24, 0x3fb8aa3b, v103
	v_fmamk_f32 v25, v25, 0x3fb8aa3b, v103
	v_fmamk_f32 v26, v26, 0x3fb8aa3b, v103
	v_fmamk_f32 v27, v27, 0x3fb8aa3b, v103
	v_fmamk_f32 v28, v28, 0x3fb8aa3b, v103
	s_waitcnt lgkmcnt(11)
	v_mfma_f32_32x32x16_bf16 v[36:51], v[130:133], v[84:87], v[36:51]
	v_fmamk_f32 v29, v29, 0x3fb8aa3b, v103
	v_fmamk_f32 v30, v30, 0x3fb8aa3b, v103
	v_fmamk_f32 v31, v31, 0x3fb8aa3b, v103
	v_fmamk_f32 v32, v32, 0x3fb8aa3b, v103
	v_fmamk_f32 v33, v33, 0x3fb8aa3b, v103
	v_fmamk_f32 v34, v34, 0x3fb8aa3b, v103
	v_fmac_f32_e32 v103, 0x3fb8aa3b, v35
	v_exp_f32_e32 v7, v7
	s_waitcnt lgkmcnt(10)
	v_mfma_f32_32x32x16_bf16 v[36:51], v[138:141], v[88:91], v[36:51]
	v_exp_f32_e32 v8, v8
	v_exp_f32_e32 v35, v103
	v_add_f32_e32 v103, 0, v4
	v_exp_f32_e32 v9, v9
	s_waitcnt lgkmcnt(9)
	v_mfma_f32_32x32x16_bf16 v[36:51], v[146:149], v[92:95], v[36:51]
	v_add_f32_e32 v103, v5, v103
	v_exp_f32_e32 v10, v10
	v_add_f32_e32 v103, v6, v103
	v_exp_f32_e32 v11, v11
	v_add_f32_e32 v103, v7, v103
	v_exp_f32_e32 v12, v12
	s_waitcnt lgkmcnt(8)
	v_mfma_f32_32x32x16_bf16 v[36:51], v[214:217], v[96:99], v[36:51]
	v_add_f32_e32 v103, v8, v103
	v_exp_f32_e32 v13, v13
	v_add_f32_e32 v103, v9, v103
	v_exp_f32_e32 v14, v14
	v_add_f32_e32 v103, v10, v103
	s_waitcnt lgkmcnt(7)
	v_mfma_f32_32x32x16_bf16 v[52:67], v[52:55], v[68:71], 0
	v_exp_f32_e32 v15, v15
	v_add_f32_e32 v103, v11, v103
	v_exp_f32_e32 v16, v16
	v_add_f32_e32 v103, v12, v103
	v_exp_f32_e32 v17, v17
	s_waitcnt lgkmcnt(6)
	v_mfma_f32_32x32x16_bf16 v[52:67], v[110:113], v[72:75], v[52:67]
	v_add_f32_e32 v103, v13, v103
	v_exp_f32_e32 v18, v18
	v_add_f32_e32 v103, v14, v103
	v_exp_f32_e32 v19, v19
	v_add_f32_e32 v103, v15, v103
	v_exp_f32_e32 v20, v20
	s_waitcnt lgkmcnt(5)
	v_mfma_f32_32x32x16_bf16 v[52:67], v[118:121], v[76:79], v[52:67]
	v_add_f32_e32 v103, v16, v103
	v_exp_f32_e32 v21, v21
	v_add_f32_e32 v103, v17, v103
	v_exp_f32_e32 v22, v22
	v_add_f32_e32 v103, v18, v103
	s_waitcnt lgkmcnt(4)
	v_mfma_f32_32x32x16_bf16 v[52:67], v[126:129], v[80:83], v[52:67]
	v_exp_f32_e32 v23, v23
	v_add_f32_e32 v103, v19, v103
	v_exp_f32_e32 v24, v24
	v_add_f32_e32 v103, v20, v103
	v_exp_f32_e32 v25, v25
	s_waitcnt lgkmcnt(3)
	v_mfma_f32_32x32x16_bf16 v[52:67], v[134:137], v[84:87], v[52:67]
	v_add_f32_e32 v103, v21, v103
	v_exp_f32_e32 v26, v26
	v_add_f32_e32 v103, v22, v103
	v_exp_f32_e32 v27, v27
	v_add_f32_e32 v103, v23, v103
	v_exp_f32_e32 v28, v28
	s_waitcnt lgkmcnt(2)
	v_mfma_f32_32x32x16_bf16 v[52:67], v[142:145], v[88:91], v[52:67]
	v_add_f32_e32 v103, v24, v103
	v_exp_f32_e32 v29, v29
	v_add_f32_e32 v103, v25, v103
	v_exp_f32_e32 v30, v30
	v_add_f32_e32 v103, v26, v103
	s_waitcnt lgkmcnt(1)
	v_mfma_f32_32x32x16_bf16 v[52:67], v[150:153], v[92:95], v[52:67]
	v_exp_f32_e32 v31, v31
	v_add_f32_e32 v103, v27, v103
	v_exp_f32_e32 v32, v32
	v_add_f32_e32 v103, v28, v103
	v_exp_f32_e32 v33, v33
	s_waitcnt lgkmcnt(0)
	v_mfma_f32_32x32x16_bf16 v[52:67], v[218:221], v[96:99], v[52:67]
	v_add_f32_e32 v103, v29, v103
	v_exp_f32_e32 v34, v34
	v_add_f32_e32 v103, v30, v103
	v_add_f32_e32 v103, v31, v103
	v_add_f32_e32 v103, v32, v103
	v_add_f32_e32 v103, v33, v103
	v_add_f32_e32 v103, v34, v103
	s_branch .Lds_join_s0

.LBB0_1370:
	v_max_f32_e32 v107, v36, v37
	v_max3_f32 v107, v107, v38, v39
	v_max3_f32 v107, v107, v40, v41
	v_max3_f32 v107, v107, v42, v43
	v_max3_f32 v107, v107, v44, v45
	v_max3_f32 v107, v107, v46, v47
	v_max3_f32 v107, v107, v48, v49
	v_max3_f32 v107, v107, v50, v51
	v_max3_f32 v107, v107, v52, v53
	v_max3_f32 v107, v107, v54, v55
	v_max3_f32 v107, v107, v56, v57
	v_max3_f32 v107, v107, v58, v59
	v_max3_f32 v107, v107, v60, v61
	v_max3_f32 v107, v107, v62, v63
	v_max3_f32 v107, v107, v64, v65
	v_max3_f32 v107, v107, v66, v67
	v_mov_b32_e32 v108, v107
	s_nop 1
	v_permlane32_swap_b32_e32 v107, v108
	v_max_f32_e32 v107, v107, v108
	v_sub_f32_e32 v108, v107, v102
	v_cmp_ge_f32_e32 vcc, s34, v108
	v_max_f32_e32 v108, v102, v107
	v_sub_f32_e32 v107, v102, v108
	v_mul_f32_e32 v107, 0x3fb8aa3b, v107
	v_exp_f32_e32 v107, v107
	s_cmp_eq_u64 vcc, exec
	s_cselect_b64 vcc, -1, 0
	s_waitcnt lgkmcnt(0)
	s_barrier
	v_cndmask_b32_e64 v107, v107, 1.0, vcc
	v_cmp_gt_f32_e64 s[0:1], 1.0, v107
	s_cmp_lg_u64 s[0:1], 0
	s_cselect_b64 s[0:1], -1, 0
	s_and_b64 s[78:79], s[0:1], s[2:3]
	s_and_saveexec_b64 s[20:21], s[78:79]
	s_cbranch_execz .LBB0_1377
	ds_write_b32 v2, v107
	s_or_b64 exec, exec, s[20:21]
	s_and_saveexec_b64 s[20:21], s[4:5]
	s_cbranch_execnz .LBB0_1378

.Lrot_exit_0:
	s_waitcnt lgkmcnt(0)
	s_barrier
.LBB0_1382:
	s_waitcnt lgkmcnt(0)
	s_barrier

.LBB0_1391:
	s_addk_i32 s6, 0x80
	s_add_i32 s60, s60, 0x8000
	s_add_i32 s58, s58, 2
	s_add_i32 s57, s57, 2
	s_add_i32 s56, s56, 2
	s_add_i32 s59, s59, 2
	s_cmp_ge_u32 s14, s36
	s_cbranch_scc1 .Lrot_exit_1
	s_waitcnt lgkmcnt(0)
	s_barrier
.LBB0_1392:
	v_max_f32_e32 v101, v4, v5
	v_max3_f32 v101, v101, v6, v7
	v_max3_f32 v101, v101, v8, v9
	v_max3_f32 v101, v101, v10, v11
	v_max3_f32 v101, v101, v12, v13
	v_max3_f32 v101, v101, v14, v15
	v_max3_f32 v101, v101, v16, v17
	v_max3_f32 v101, v101, v18, v19
	v_max3_f32 v101, v101, v20, v21
	v_max3_f32 v101, v101, v22, v23
	v_max3_f32 v101, v101, v24, v25
	v_max3_f32 v101, v101, v26, v27
	v_max3_f32 v101, v101, v28, v29
	v_max3_f32 v101, v101, v30, v31
	v_max3_f32 v101, v101, v32, v33
	v_max3_f32 v101, v101, v34, v35
	v_mov_b32_e32 v103, v101
	s_nop 1
	v_permlane32_swap_b32_e32 v101, v103
	v_max_f32_e32 v101, v101, v103
	v_sub_f32_e32 v103, v101, v102
	v_cmp_ge_f32_e32 vcc, s34, v103
	v_max_f32_e32 v103, v102, v101
	v_sub_f32_e32 v101, v102, v103
	v_mul_f32_e32 v101, 0x3fb8aa3b, v101
	v_exp_f32_e32 v101, v101
	s_cmp_eq_u64 vcc, exec
	s_cselect_b64 vcc, -1, 0
	v_cndmask_b32_e64 v101, v101, 1.0, vcc
	v_cmp_gt_f32_e64 s[0:1], 1.0, v101
	s_cmp_lg_u64 s[0:1], 0
	s_cselect_b64 s[0:1], -1, 0
	s_and_b64 s[66:67], s[0:1], s[2:3]
	s_and_saveexec_b64 s[14:15], s[66:67]
	ds_write_b32 v2, v101
	s_or_b64 exec, exec, s[14:15]
	s_and_saveexec_b64 s[14:15], s[4:5]
	v_cndmask_b32_e64 v104, 0, 1, s[0:1]
	s_add_i32 s0, s19, 0
	s_add_i32 s0, s0, 0x20000
	v_mov_b32_e32 v105, s0
	ds_write_b32 v105, v104
	s_or_b64 exec, exec, s[14:15]
	s_add_i32 s0, s58, -3
	s_cmp_ge_u32 s0, s36
	v_add_u32_e32 v104, s60, v184
	s_cbranch_scc1 .LBB0_1398
	s_mul_hi_u32 s0, s56, 0xaaaaaaab
	s_lshr_b32 s0, s0, 1
	s_mul_i32 s0, s0, 0xc000
	s_sub_i32 s98, s60, s0
	v_add_u32_e32 v251, s98, v184
	v_add_u32_e32 v47, v251, v190
	v_add_u32_e32 v40, v251, v192
	v_add_u32_e32 v41, v251, v194
	v_add_u32_e32 v42, v251, v196
	v_add_u32_e32 v43, v251, v198
	v_add_u32_e32 v44, v251, v200
	v_add_u32_e32 v45, v251, v202
	v_add_u32_e32 v46, v251, v203
	ds_read_b128 v[36:39], v47
	ds_read_b128 v[106:109], v40
	ds_read_b128 v[114:117], v41
	ds_read_b128 v[122:125], v42
	ds_read_b128 v[130:133], v43
	ds_read_b128 v[138:141], v44
	ds_read_b128 v[146:149], v45
	ds_read_b128 v[154:157], v46
	ds_read_b128 v[52:55], v47 offset:8192
	ds_read_b128 v[110:113], v40 offset:8192
	ds_read_b128 v[118:121], v41 offset:8192
	ds_read_b128 v[126:129], v42 offset:8192
	ds_read_b128 v[134:137], v43 offset:8192
	ds_read_b128 v[142:145], v44 offset:8192
	ds_read_b128 v[150:153], v45 offset:8192
	ds_read_b128 v[214:217], v46 offset:8192
	s_waitcnt lgkmcnt(14)
	v_mfma_f32_32x32x16_bf16 v[36:51], v[36:39], v[68:71], 0
	v_cndmask_b32_e32 v102, v103, v102, vcc
	v_mul_f32_e32 v103, 0xbfb8aa3b, v102
	v_fmamk_f32 v4, v4, 0x3fb8aa3b, v103
	v_fmamk_f32 v5, v5, 0x3fb8aa3b, v103
	v_exp_f32_e32 v4, v4
	v_fmamk_f32 v6, v6, 0x3fb8aa3b, v103
	v_exp_f32_e32 v5, v5
	v_mfma_f32_32x32x16_bf16 v[36:51], v[106:109], v[72:75], v[36:51]
	v_fmamk_f32 v7, v7, 0x3fb8aa3b, v103
	v_exp_f32_e32 v6, v6
	v_fmamk_f32 v8, v8, 0x3fb8aa3b, v103
	v_fmamk_f32 v9, v9, 0x3fb8aa3b, v103
	v_fmamk_f32 v10, v10, 0x3fb8aa3b, v103
	v_fmamk_f32 v11, v11, 0x3fb8aa3b, v103
	v_fmamk_f32 v12, v12, 0x3fb8aa3b, v103
	s_waitcnt lgkmcnt(13)
	v_mfma_f32_32x32x16_bf16 v[36:51], v[114:117], v[76:79], v[36:51]
	v_fmamk_f32 v13, v13, 0x3fb8aa3b, v103
	v_fmamk_f32 v14, v14, 0x3fb8aa3b, v103
	v_fmamk_f32 v15, v15, 0x3fb8aa3b, v103
	v_fmamk_f32 v16, v16, 0x3fb8aa3b, v103
	v_fmamk_f32 v17, v17, 0x3fb8aa3b, v103
	v_fmamk_f32 v18, v18, 0x3fb8aa3b, v103
	v_fmamk_f32 v19, v19, 0x3fb8aa3b, v103
	v_fmamk_f32 v20, v20, 0x3fb8aa3b, v103
	s_waitcnt lgkmcnt(12)
	v_mfma_f32_32x32x16_bf16 v[36:51], v[122:125], v[80:83], v[36:51]
	v_fmamk_f32 v21, v21, 0x3fb8aa3b, v103
	v_fmamk_f32 v22, v22, 0x3fb8aa3b, v103
	v_fmamk_f32 v23, v23, 0x3fb8aa3b, v103
	v_fmamk_f32 v24, v24, 0x3fb8aa3b, v103
	v_fmamk_f32 v25, v25, 0x3fb8aa3b, v103
	v_fmamk_f32 v26, v26, 0x3fb8aa3b, v103
	v_fmamk_f32 v27, v27, 0x3fb8aa3b, v103
	v_fmamk_f32 v28, v28, 0x3fb8aa3b, v103
	s_waitcnt lgkmcnt(11)
	v_mfma_f32_32x32x16_bf16 v[36:51], v[130:133], v[84:87], v[36:51]
	v_fmamk_f32 v29, v29, 0x3fb8aa3b, v103
	v_fmamk_f32 v30, v30, 0x3fb8aa3b, v103
	v_fmamk_f32 v31, v31, 0x3fb8aa3b, v103
	v_fmamk_f32 v32, v32, 0x3fb8aa3b, v103
	v_fmamk_f32 v33, v33, 0x3fb8aa3b, v103
	v_fmamk_f32 v34, v34, 0x3fb8aa3b, v103
	v_fmac_f32_e32 v103, 0x3fb8aa3b, v35
	v_exp_f32_e32 v7, v7
	s_waitcnt lgkmcnt(10)
	v_mfma_f32_32x32x16_bf16 v[36:51], v[138:141], v[88:91], v[36:51]
	v_exp_f32_e32 v8, v8
	v_exp_f32_e32 v35, v103
	v_add_f32_e32 v103, 0, v4
	v_exp_f32_e32 v9, v9
	s_waitcnt lgkmcnt(9)
	v_mfma_f32_32x32x16_bf16 v[36:51], v[146:149], v[92:95], v[36:51]
	v_add_f32_e32 v103, v5, v103
	v_exp_f32_e32 v10, v10
	v_add_f32_e32 v103, v6, v103
	v_exp_f32_e32 v11, v11
	v_add_f32_e32 v103, v7, v103
	v_exp_f32_e32 v12, v12
	s_waitcnt lgkmcnt(8)
	v_mfma_f32_32x32x16_bf16 v[36:51], v[154:157], v[96:99], v[36:51]
	v_add_f32_e32 v103, v8, v103
	v_exp_f32_e32 v13, v13
	v_add_f32_e32 v103, v9, v103
	v_exp_f32_e32 v14, v14
	v_add_f32_e32 v103, v10, v103
	s_waitcnt lgkmcnt(7)
	v_mfma_f32_32x32x16_bf16 v[52:67], v[52:55], v[68:71], 0
	v_exp_f32_e32 v15, v15
	v_add_f32_e32 v103, v11, v103
	v_exp_f32_e32 v16, v16
	v_add_f32_e32 v103, v12, v103
	v_exp_f32_e32 v17, v17
	s_waitcnt lgkmcnt(6)
	v_mfma_f32_32x32x16_bf16 v[52:67], v[110:113], v[72:75], v[52:67]
	v_add_f32_e32 v103, v13, v103
	v_exp_f32_e32 v18, v18
	v_add_f32_e32 v103, v14, v103
	v_exp_f32_e32 v19, v19
	v_add_f32_e32 v103, v15, v103
	v_exp_f32_e32 v20, v20
	s_waitcnt lgkmcnt(5)
	v_mfma_f32_32x32x16_bf16 v[52:67], v[118:121], v[76:79], v[52:67]
	v_add_f32_e32 v103, v16, v103
	v_exp_f32_e32 v21, v21
	v_add_f32_e32 v103, v17, v103
	v_exp_f32_e32 v22, v22
	v_add_f32_e32 v103, v18, v103
	s_waitcnt lgkmcnt(4)
	v_mfma_f32_32x32x16_bf16 v[52:67], v[126:129], v[80:83], v[52:67]
	v_exp_f32_e32 v23, v23
	v_add_f32_e32 v103, v19, v103
	v_exp_f32_e32 v24, v24
	v_add_f32_e32 v103, v20, v103
	v_exp_f32_e32 v25, v25
	s_waitcnt lgkmcnt(3)
	v_mfma_f32_32x32x16_bf16 v[52:67], v[134:137], v[84:87], v[52:67]
	v_add_f32_e32 v103, v21, v103
	v_exp_f32_e32 v26, v26
	v_add_f32_e32 v103, v22, v103
	v_exp_f32_e32 v27, v27
	v_add_f32_e32 v103, v23, v103
	v_exp_f32_e32 v28, v28
	s_waitcnt lgkmcnt(2)
	v_mfma_f32_32x32x16_bf16 v[52:67], v[142:145], v[88:91], v[52:67]
	v_add_f32_e32 v103, v24, v103
	v_exp_f32_e32 v29, v29
	v_add_f32_e32 v103, v25, v103
	v_exp_f32_e32 v30, v30
	v_add_f32_e32 v103, v26, v103
	s_waitcnt lgkmcnt(1)
	v_mfma_f32_32x32x16_bf16 v[52:67], v[150:153], v[92:95], v[52:67]
	v_exp_f32_e32 v31, v31
	v_add_f32_e32 v103, v27, v103
	v_exp_f32_e32 v32, v32
	v_add_f32_e32 v103, v28, v103
	v_exp_f32_e32 v33, v33
	s_waitcnt lgkmcnt(0)
	v_mfma_f32_32x32x16_bf16 v[52:67], v[214:217], v[96:99], v[52:67]
	v_add_f32_e32 v103, v29, v103
	v_exp_f32_e32 v34, v34
	v_add_f32_e32 v103, v30, v103
	v_add_f32_e32 v103, v31, v103
	v_add_f32_e32 v103, v32, v103
	v_add_f32_e32 v103, v33, v103
	v_add_f32_e32 v103, v34, v103
	s_branch .Lds_join_s2

.LBB0_1402:
	v_max_f32_e32 v107, v36, v37
	v_max3_f32 v107, v107, v38, v39
	v_max3_f32 v107, v107, v40, v41
	v_max3_f32 v107, v107, v42, v43
	v_max3_f32 v107, v107, v44, v45
	v_max3_f32 v107, v107, v46, v47
	v_max3_f32 v107, v107, v48, v49
	v_max3_f32 v107, v107, v50, v51
	v_max3_f32 v107, v107, v52, v53
	v_max3_f32 v107, v107, v54, v55
	v_max3_f32 v107, v107, v56, v57
	v_max3_f32 v107, v107, v58, v59
	v_max3_f32 v107, v107, v60, v61
	v_max3_f32 v107, v107, v62, v63
	v_max3_f32 v107, v107, v64, v65
	v_max3_f32 v107, v107, v66, v67
	v_mov_b32_e32 v108, v107
	s_nop 1
	v_permlane32_swap_b32_e32 v107, v108
	v_max_f32_e32 v107, v107, v108
	v_sub_f32_e32 v108, v107, v102
	v_cmp_ge_f32_e32 vcc, s34, v108
	v_max_f32_e32 v108, v102, v107
	v_sub_f32_e32 v107, v102, v108
	v_mul_f32_e32 v107, 0x3fb8aa3b, v107
	v_exp_f32_e32 v107, v107
	s_cmp_eq_u64 vcc, exec
	s_cselect_b64 vcc, -1, 0
	s_waitcnt lgkmcnt(0)
	s_barrier
	v_cndmask_b32_e64 v107, v107, 1.0, vcc
	v_cmp_gt_f32_e64 s[0:1], 1.0, v107
	s_cmp_lg_u64 s[0:1], 0
	s_cselect_b64 s[0:1], -1, 0
	s_and_b64 s[66:67], s[0:1], s[2:3]
	s_and_saveexec_b64 s[14:15], s[66:67]
	s_cbranch_execz .LBB0_1409
	ds_write_b32 v2, v107
	s_or_b64 exec, exec, s[14:15]
	s_and_saveexec_b64 s[14:15], s[4:5]
	s_cbranch_execnz .LBB0_1410

.Lrot_exit_1:
	s_waitcnt lgkmcnt(0)
	s_barrier
	s_branch .LBB0_1334
